# MLP-in (relu^2) epilogue stores of U also write-through (sc1)
# baseline (speedup 1.0000x reference)
.LBB0_1340:
	v_lshl_add_u32 v142, s48, 8, v146
	v_ashrrev_i32_e32 v143, 31, v142
	v_lshlrev_b64 v[144:145], 14, v[142:143]
	ds_read_b32 v143, v148
	v_max_f32_e32 v122, v122, v122
	v_max_f32_e32 v122, 0, v122
	v_max_f32_e32 v123, v123, v123
	v_max_f32_e32 v124, v124, v124
	s_waitcnt lgkmcnt(0)
	v_mul_f32_e32 v122, v122, v143
	v_max_f32_e32 v123, 0, v123
	v_max_f32_e32 v124, 0, v124
	v_mul_f32_e32 v151, v122, v122
	v_max_f32_e32 v122, v127, v127
	v_mul_f32_e32 v123, v123, v143
	v_mul_f32_e32 v124, v124, v143
	v_lshl_or_b32 v140, s28, 8, v149
	v_max_f32_e32 v126, v126, v126
	v_max_f32_e32 v122, 0, v122
	v_mul_f32_e32 v127, v123, v123
	v_max_f32_e32 v123, v128, v128
	v_mul_f32_e32 v128, v124, v124
	v_max_f32_e32 v124, v129, v129
	v_max_f32_e32 v125, v125, v125
	v_ashrrev_i32_e32 v141, 31, v140
	v_max_f32_e32 v126, 0, v126
	v_mul_f32_e32 v122, v122, v143
	v_max_f32_e32 v123, 0, v123
	v_max_f32_e32 v124, 0, v124
	v_max_f32_e32 v125, 0, v125
	v_max_f32_e32 v114, v114, v114
	v_max_f32_e32 v115, v115, v115
	v_max_f32_e32 v116, v116, v116
	v_lshl_add_u64 v[152:153], s[18:19], 0, v[144:145]
	v_lshlrev_b64 v[144:145], 1, v[140:141]
	v_mul_f32_e32 v126, v126, v143
	v_mul_f32_e32 v122, v122, v122
	v_mul_f32_e32 v123, v123, v143
	v_mul_f32_e32 v124, v124, v143
	v_mul_f32_e32 v125, v125, v143
	v_max_f32_e32 v114, 0, v114
	v_max_f32_e32 v115, 0, v115
	v_max_f32_e32 v116, 0, v116
	v_lshl_add_u64 v[140:141], v[152:153], 0, v[144:145]
	v_mul_f32_e32 v126, v126, v126
	v_mul_f32_e32 v123, v123, v123
	v_mul_f32_e32 v124, v124, v124
	v_mul_f32_e32 v125, v125, v125
	v_cvt_pk_bf16_f32 v122, v126, v122
	v_mul_f32_e32 v114, v114, v143
	v_mul_f32_e32 v115, v115, v143
	v_mul_f32_e32 v116, v116, v143
	v_cvt_pk_bf16_f32 v123, v123, v124
	v_cvt_pk_bf16_f32 v124, v151, v127
	v_cvt_pk_bf16_f32 v125, v128, v125
	global_store_dwordx4 v[140:141], v[122:125], off sc1
	v_max_f32_e32 v118, v118, v118
	v_max_f32_e32 v117, v117, v117
	v_mul_f32_e32 v122, v114, v114
	v_max_f32_e32 v114, v119, v119
	v_mul_f32_e32 v119, v115, v115
	v_max_f32_e32 v115, v120, v120
	v_mul_f32_e32 v120, v116, v116
	v_max_f32_e32 v116, v121, v121
	v_max_f32_e32 v114, 0, v114
	v_max_f32_e32 v115, 0, v115
	v_max_f32_e32 v116, 0, v116
	v_max_f32_e32 v118, 0, v118
	v_mul_f32_e32 v114, v114, v143
	v_mul_f32_e32 v115, v115, v143
	v_mul_f32_e32 v116, v116, v143
	v_max_f32_e32 v117, 0, v117
	v_mul_f32_e32 v118, v118, v143
	v_mul_f32_e32 v114, v114, v114
	v_mul_f32_e32 v115, v115, v115
	v_mul_f32_e32 v117, v117, v143
	v_mul_f32_e32 v116, v116, v116
	v_mul_f32_e32 v118, v118, v118
	v_mul_f32_e32 v117, v117, v117
	v_cvt_pk_bf16_f32 v114, v118, v114
	v_cvt_pk_bf16_f32 v115, v115, v116
	v_cvt_pk_bf16_f32 v116, v122, v119
	v_cvt_pk_bf16_f32 v117, v120, v117
	global_store_dwordx4 v[140:141], v[114:117], off offset:256 sc1
	ds_read_b32 v116, v148 offset:64
	v_max_f32_e32 v106, v106, v106
	v_max_f32_e32 v106, 0, v106
	v_max_f32_e32 v107, v107, v107
	v_max_f32_e32 v108, v108, v108
	s_waitcnt lgkmcnt(0)
	v_mul_f32_e32 v106, v106, v116
	v_max_f32_e32 v107, 0, v107
	v_max_f32_e32 v108, 0, v108
	v_or_b32_e32 v114, 16, v142
	v_mul_f32_e32 v117, v106, v106
	v_max_f32_e32 v106, v111, v111
	v_mul_f32_e32 v107, v107, v116
	v_mul_f32_e32 v108, v108, v116
	v_ashrrev_i32_e32 v115, 31, v114
	v_max_f32_e32 v110, v110, v110
	v_max_f32_e32 v106, 0, v106
	v_mul_f32_e32 v111, v107, v107
	v_max_f32_e32 v107, v112, v112
	v_mul_f32_e32 v112, v108, v108
	v_max_f32_e32 v108, v113, v113
	v_max_f32_e32 v109, v109, v109
	v_lshlrev_b64 v[114:115], 14, v[114:115]
	v_max_f32_e32 v110, 0, v110
	v_mul_f32_e32 v106, v106, v116
	v_max_f32_e32 v107, 0, v107
	v_max_f32_e32 v108, 0, v108
	v_max_f32_e32 v109, 0, v109
	v_max_f32_e32 v98, v98, v98
	v_max_f32_e32 v99, v99, v99
	v_max_f32_e32 v100, v100, v100
	v_lshl_add_u64 v[114:115], s[18:19], 0, v[114:115]
	v_mul_f32_e32 v110, v110, v116
	v_mul_f32_e32 v106, v106, v106
	v_mul_f32_e32 v107, v107, v116
	v_mul_f32_e32 v108, v108, v116
	v_mul_f32_e32 v109, v109, v116
	v_max_f32_e32 v98, 0, v98
	v_max_f32_e32 v99, 0, v99
	v_max_f32_e32 v100, 0, v100
	v_lshl_add_u64 v[114:115], v[114:115], 0, v[144:145]
	v_mul_f32_e32 v110, v110, v110
	v_mul_f32_e32 v107, v107, v107
	v_mul_f32_e32 v108, v108, v108
	v_mul_f32_e32 v109, v109, v109
	v_cvt_pk_bf16_f32 v106, v110, v106
	v_mul_f32_e32 v98, v98, v116
	v_mul_f32_e32 v99, v99, v116
	v_mul_f32_e32 v100, v100, v116
	v_cvt_pk_bf16_f32 v107, v107, v108
	v_cvt_pk_bf16_f32 v108, v117, v111
	v_cvt_pk_bf16_f32 v109, v112, v109
	global_store_dwordx4 v[114:115], v[106:109], off sc1
	v_max_f32_e32 v102, v102, v102
	v_max_f32_e32 v101, v101, v101
	v_mul_f32_e32 v106, v98, v98
	v_max_f32_e32 v98, v103, v103
	v_mul_f32_e32 v103, v99, v99
	v_max_f32_e32 v99, v104, v104
	v_mul_f32_e32 v104, v100, v100
	v_max_f32_e32 v100, v105, v105
	v_max_f32_e32 v98, 0, v98
	v_max_f32_e32 v99, 0, v99
	v_max_f32_e32 v100, 0, v100
	v_max_f32_e32 v102, 0, v102
	v_mul_f32_e32 v98, v98, v116
	v_mul_f32_e32 v99, v99, v116
	v_mul_f32_e32 v100, v100, v116
	v_max_f32_e32 v101, 0, v101
	v_mul_f32_e32 v102, v102, v116
	v_mul_f32_e32 v98, v98, v98
	v_mul_f32_e32 v99, v99, v99
	v_mul_f32_e32 v101, v101, v116
	v_mul_f32_e32 v100, v100, v100
	v_mul_f32_e32 v102, v102, v102
	v_mul_f32_e32 v101, v101, v101
	v_cvt_pk_bf16_f32 v98, v102, v98
	v_cvt_pk_bf16_f32 v99, v99, v100
	v_cvt_pk_bf16_f32 v100, v106, v103
	v_cvt_pk_bf16_f32 v101, v104, v101
	global_store_dwordx4 v[114:115], v[98:101], off offset:256 sc1
	ds_read_b32 v100, v148 offset:128
	v_max_f32_e32 v90, v90, v90
	v_max_f32_e32 v90, 0, v90
	v_max_f32_e32 v91, v91, v91
	v_max_f32_e32 v92, v92, v92
	s_waitcnt lgkmcnt(0)
	v_mul_f32_e32 v90, v90, v100
	v_max_f32_e32 v91, 0, v91
	v_max_f32_e32 v92, 0, v92
	v_or_b32_e32 v98, 32, v142
	v_mul_f32_e32 v101, v90, v90
	v_max_f32_e32 v90, v95, v95
	v_mul_f32_e32 v91, v91, v100
	v_mul_f32_e32 v92, v92, v100
	v_ashrrev_i32_e32 v99, 31, v98
	v_max_f32_e32 v94, v94, v94
	v_max_f32_e32 v90, 0, v90
	v_mul_f32_e32 v95, v91, v91
	v_max_f32_e32 v91, v96, v96
	v_mul_f32_e32 v96, v92, v92
	v_max_f32_e32 v92, v97, v97
	v_max_f32_e32 v93, v93, v93
	v_lshlrev_b64 v[98:99], 14, v[98:99]
	v_max_f32_e32 v94, 0, v94
	v_mul_f32_e32 v90, v90, v100
	v_max_f32_e32 v91, 0, v91
	v_max_f32_e32 v92, 0, v92
	v_max_f32_e32 v93, 0, v93
	v_max_f32_e32 v82, v82, v82
	v_max_f32_e32 v83, v83, v83
	v_max_f32_e32 v84, v84, v84
	v_lshl_add_u64 v[98:99], s[18:19], 0, v[98:99]
	v_mul_f32_e32 v94, v94, v100
	v_mul_f32_e32 v90, v90, v90
	v_mul_f32_e32 v91, v91, v100
	v_mul_f32_e32 v92, v92, v100
	v_mul_f32_e32 v93, v93, v100
	v_max_f32_e32 v82, 0, v82
	v_max_f32_e32 v83, 0, v83
	v_max_f32_e32 v84, 0, v84
	v_lshl_add_u64 v[98:99], v[98:99], 0, v[144:145]
	v_mul_f32_e32 v94, v94, v94
	v_mul_f32_e32 v91, v91, v91
	v_mul_f32_e32 v92, v92, v92
	v_mul_f32_e32 v93, v93, v93
	v_cvt_pk_bf16_f32 v90, v94, v90
	v_mul_f32_e32 v82, v82, v100
	v_mul_f32_e32 v83, v83, v100
	v_mul_f32_e32 v84, v84, v100
	v_cvt_pk_bf16_f32 v91, v91, v92
	v_cvt_pk_bf16_f32 v92, v101, v95
	v_cvt_pk_bf16_f32 v93, v96, v93
	global_store_dwordx4 v[98:99], v[90:93], off sc1
	v_max_f32_e32 v86, v86, v86
	v_max_f32_e32 v85, v85, v85
	v_mul_f32_e32 v90, v82, v82
	v_max_f32_e32 v82, v87, v87
	v_mul_f32_e32 v87, v83, v83
	v_max_f32_e32 v83, v88, v88
	v_mul_f32_e32 v88, v84, v84
	v_max_f32_e32 v84, v89, v89
	v_max_f32_e32 v82, 0, v82
	v_max_f32_e32 v83, 0, v83
	v_max_f32_e32 v84, 0, v84
	v_max_f32_e32 v86, 0, v86
	v_mul_f32_e32 v82, v82, v100
	v_mul_f32_e32 v83, v83, v100
	v_mul_f32_e32 v84, v84, v100
	v_max_f32_e32 v85, 0, v85
	v_mul_f32_e32 v86, v86, v100
	v_mul_f32_e32 v82, v82, v82
	v_mul_f32_e32 v83, v83, v83
	v_mul_f32_e32 v85, v85, v100
	v_mul_f32_e32 v84, v84, v84
	v_mul_f32_e32 v86, v86, v86
	v_mul_f32_e32 v85, v85, v85
	v_cvt_pk_bf16_f32 v82, v86, v82
	v_cvt_pk_bf16_f32 v83, v83, v84
	v_cvt_pk_bf16_f32 v84, v90, v87
	v_cvt_pk_bf16_f32 v85, v88, v85
	global_store_dwordx4 v[98:99], v[82:85], off offset:256 sc1
	ds_read_b32 v84, v148 offset:192
	v_max_f32_e32 v74, v74, v74
	v_max_f32_e32 v74, 0, v74
	v_max_f32_e32 v75, v75, v75
	v_max_f32_e32 v76, v76, v76
	s_waitcnt lgkmcnt(0)
	v_mul_f32_e32 v74, v74, v84
	v_max_f32_e32 v75, 0, v75
	v_max_f32_e32 v76, 0, v76
	v_or_b32_e32 v82, 48, v142
	v_mul_f32_e32 v85, v74, v74
	v_max_f32_e32 v74, v79, v79
	v_mul_f32_e32 v75, v75, v84
	v_mul_f32_e32 v76, v76, v84
	v_ashrrev_i32_e32 v83, 31, v82
	v_max_f32_e32 v78, v78, v78
	v_max_f32_e32 v74, 0, v74
	v_mul_f32_e32 v79, v75, v75
	v_max_f32_e32 v75, v80, v80
	v_mul_f32_e32 v80, v76, v76
	v_max_f32_e32 v76, v81, v81
	v_max_f32_e32 v77, v77, v77
	v_lshlrev_b64 v[82:83], 14, v[82:83]
	v_max_f32_e32 v78, 0, v78
	v_mul_f32_e32 v74, v74, v84
	v_max_f32_e32 v75, 0, v75
	v_max_f32_e32 v76, 0, v76
	v_max_f32_e32 v77, 0, v77
	v_max_f32_e32 v66, v66, v66
	v_max_f32_e32 v67, v67, v67
	v_max_f32_e32 v68, v68, v68
	v_lshl_add_u64 v[82:83], s[18:19], 0, v[82:83]
	v_mul_f32_e32 v78, v78, v84
	v_mul_f32_e32 v74, v74, v74
	v_mul_f32_e32 v75, v75, v84
	v_mul_f32_e32 v76, v76, v84
	v_mul_f32_e32 v77, v77, v84
	v_max_f32_e32 v66, 0, v66
	v_max_f32_e32 v67, 0, v67
	v_max_f32_e32 v68, 0, v68
	v_lshl_add_u64 v[82:83], v[82:83], 0, v[144:145]
	v_mul_f32_e32 v78, v78, v78
	v_mul_f32_e32 v75, v75, v75
	v_mul_f32_e32 v76, v76, v76
	v_mul_f32_e32 v77, v77, v77
	v_cvt_pk_bf16_f32 v74, v78, v74
	v_mul_f32_e32 v66, v66, v84
	v_mul_f32_e32 v67, v67, v84
	v_mul_f32_e32 v68, v68, v84
	v_cvt_pk_bf16_f32 v75, v75, v76
	v_cvt_pk_bf16_f32 v76, v85, v79
	v_cvt_pk_bf16_f32 v77, v80, v77
	global_store_dwordx4 v[82:83], v[74:77], off sc1
	v_max_f32_e32 v70, v70, v70
	v_max_f32_e32 v69, v69, v69
	v_mul_f32_e32 v74, v66, v66
	v_max_f32_e32 v66, v71, v71
	v_mul_f32_e32 v71, v67, v67
	v_max_f32_e32 v67, v72, v72
	v_mul_f32_e32 v72, v68, v68
	v_max_f32_e32 v68, v73, v73
	v_max_f32_e32 v66, 0, v66
	v_max_f32_e32 v67, 0, v67
	v_max_f32_e32 v68, 0, v68
	v_max_f32_e32 v70, 0, v70
	v_mul_f32_e32 v66, v66, v84
	v_mul_f32_e32 v67, v67, v84
	v_mul_f32_e32 v68, v68, v84
	v_max_f32_e32 v69, 0, v69
	v_mul_f32_e32 v70, v70, v84
	v_mul_f32_e32 v66, v66, v66
	v_mul_f32_e32 v67, v67, v67
	v_mul_f32_e32 v69, v69, v84
	v_mul_f32_e32 v68, v68, v68
	v_mul_f32_e32 v70, v70, v70
	v_mul_f32_e32 v69, v69, v69
	v_cvt_pk_bf16_f32 v66, v70, v66
	v_cvt_pk_bf16_f32 v67, v67, v68
	v_cvt_pk_bf16_f32 v68, v74, v71
	v_cvt_pk_bf16_f32 v69, v72, v69
	global_store_dwordx4 v[82:83], v[66:69], off offset:256 sc1
	ds_read_b32 v68, v148 offset:512
	v_max_f32_e32 v58, v58, v58
	v_max_f32_e32 v58, 0, v58
	v_max_f32_e32 v59, v59, v59
	v_max_f32_e32 v60, v60, v60
	s_waitcnt lgkmcnt(0)
	v_mul_f32_e32 v58, v58, v68
	v_max_f32_e32 v59, 0, v59
	v_max_f32_e32 v60, 0, v60
	v_max_f32_e32 v62, v62, v62
	v_mul_f32_e32 v69, v58, v58
	v_max_f32_e32 v58, v63, v63
	v_mul_f32_e32 v59, v59, v68
	v_mul_f32_e32 v60, v60, v68
	v_max_f32_e32 v62, 0, v62
	v_max_f32_e32 v58, 0, v58
	v_mul_f32_e32 v63, v59, v59
	v_max_f32_e32 v59, v64, v64
	v_mul_f32_e32 v64, v60, v60
	v_max_f32_e32 v60, v65, v65
	s_mov_b64 s[4:5], 0x200000
	v_mul_f32_e32 v62, v62, v68
	v_mul_f32_e32 v58, v58, v68
	v_max_f32_e32 v59, 0, v59
	v_max_f32_e32 v60, 0, v60
	v_max_f32_e32 v61, v61, v61
	v_lshl_add_u64 v[66:67], v[140:141], 0, s[4:5]
	v_mul_f32_e32 v62, v62, v62
	v_mul_f32_e32 v58, v58, v58
	v_mul_f32_e32 v59, v59, v68
	v_mul_f32_e32 v60, v60, v68
	v_max_f32_e32 v61, 0, v61
	s_mov_b32 s4, 0x200000
	v_max_f32_e32 v50, v50, v50
	v_max_f32_e32 v51, v51, v51
	v_max_f32_e32 v52, v52, v52
	v_mul_f32_e32 v59, v59, v59
	v_mul_f32_e32 v61, v61, v68
	v_mul_f32_e32 v60, v60, v60
	v_cvt_pk_bf16_f32 v58, v62, v58
	v_add_co_u32_e32 v62, vcc, s4, v140
	v_max_f32_e32 v50, 0, v50
	v_max_f32_e32 v51, 0, v51
	v_max_f32_e32 v52, 0, v52
	v_mul_f32_e32 v61, v61, v61
	v_cvt_pk_bf16_f32 v59, v59, v60
	v_cvt_pk_bf16_f32 v60, v69, v63
	v_addc_co_u32_e32 v63, vcc, 0, v141, vcc
	v_mul_f32_e32 v50, v50, v68
	v_mul_f32_e32 v51, v51, v68
	v_mul_f32_e32 v52, v52, v68
	v_cvt_pk_bf16_f32 v61, v64, v61
	global_store_dwordx4 v[62:63], v[58:61], off sc1
	v_max_f32_e32 v54, v54, v54
	v_max_f32_e32 v53, v53, v53
	v_mul_f32_e32 v58, v50, v50
	v_max_f32_e32 v50, v55, v55
	v_mul_f32_e32 v55, v51, v51
	v_max_f32_e32 v51, v56, v56
	v_mul_f32_e32 v56, v52, v52
	v_max_f32_e32 v52, v57, v57
	v_max_f32_e32 v50, 0, v50
	v_max_f32_e32 v51, 0, v51
	v_max_f32_e32 v52, 0, v52
	v_max_f32_e32 v54, 0, v54
	v_mul_f32_e32 v50, v50, v68
	v_mul_f32_e32 v51, v51, v68
	v_mul_f32_e32 v52, v52, v68
	v_max_f32_e32 v53, 0, v53
	v_mul_f32_e32 v54, v54, v68
	v_mul_f32_e32 v50, v50, v50
	v_mul_f32_e32 v51, v51, v51
	v_mul_f32_e32 v53, v53, v68
	v_mul_f32_e32 v52, v52, v52
	v_mul_f32_e32 v54, v54, v54
	v_mul_f32_e32 v53, v53, v53
	v_cvt_pk_bf16_f32 v50, v54, v50
	v_cvt_pk_bf16_f32 v51, v51, v52
	v_cvt_pk_bf16_f32 v52, v58, v55
	v_cvt_pk_bf16_f32 v53, v56, v53
	global_store_dwordx4 v[66:67], v[50:53], off offset:256 sc1
	ds_read_b32 v52, v148 offset:576
	v_max_f32_e32 v42, v42, v42
	v_max_f32_e32 v42, 0, v42
	v_max_f32_e32 v43, v43, v43
	v_max_f32_e32 v44, v44, v44
	s_waitcnt lgkmcnt(0)
	v_mul_f32_e32 v42, v42, v52
	v_max_f32_e32 v43, 0, v43
	v_max_f32_e32 v44, 0, v44
	v_max_f32_e32 v46, v46, v46
	v_mul_f32_e32 v53, v42, v42
	v_max_f32_e32 v42, v47, v47
	v_mul_f32_e32 v43, v43, v52
	v_mul_f32_e32 v44, v44, v52
	v_max_f32_e32 v46, 0, v46
	v_max_f32_e32 v42, 0, v42
	v_mul_f32_e32 v47, v43, v43
	v_max_f32_e32 v43, v48, v48
	v_mul_f32_e32 v48, v44, v44
	v_max_f32_e32 v44, v49, v49
	s_mov_b64 s[4:5], 0x240000
	v_mul_f32_e32 v46, v46, v52
	v_mul_f32_e32 v42, v42, v52
	v_max_f32_e32 v43, 0, v43
	v_max_f32_e32 v44, 0, v44
	v_max_f32_e32 v45, v45, v45
	v_lshl_add_u64 v[50:51], v[140:141], 0, s[4:5]
	v_mul_f32_e32 v46, v46, v46
	v_mul_f32_e32 v42, v42, v42
	v_mul_f32_e32 v43, v43, v52
	v_mul_f32_e32 v44, v44, v52
	v_max_f32_e32 v45, 0, v45
	s_mov_b32 s4, 0x240000
	v_max_f32_e32 v34, v34, v34
	v_max_f32_e32 v35, v35, v35
	v_max_f32_e32 v36, v36, v36
	v_mul_f32_e32 v43, v43, v43
	v_mul_f32_e32 v45, v45, v52
	v_mul_f32_e32 v44, v44, v44
	v_cvt_pk_bf16_f32 v42, v46, v42
	v_add_co_u32_e32 v46, vcc, s4, v140
	v_max_f32_e32 v34, 0, v34
	v_max_f32_e32 v35, 0, v35
	v_max_f32_e32 v36, 0, v36
	v_mul_f32_e32 v45, v45, v45
	v_cvt_pk_bf16_f32 v43, v43, v44
	v_cvt_pk_bf16_f32 v44, v53, v47
	v_addc_co_u32_e32 v47, vcc, 0, v141, vcc
	v_mul_f32_e32 v34, v34, v52
	v_mul_f32_e32 v35, v35, v52
	v_mul_f32_e32 v36, v36, v52
	v_cvt_pk_bf16_f32 v45, v48, v45
	global_store_dwordx4 v[46:47], v[42:45], off sc1
	v_max_f32_e32 v38, v38, v38
	v_max_f32_e32 v37, v37, v37
	v_mul_f32_e32 v42, v34, v34
	v_max_f32_e32 v34, v39, v39
	v_mul_f32_e32 v39, v35, v35
	v_max_f32_e32 v35, v40, v40
	v_mul_f32_e32 v40, v36, v36
	v_max_f32_e32 v36, v41, v41
	v_max_f32_e32 v34, 0, v34
	v_max_f32_e32 v35, 0, v35
	v_max_f32_e32 v36, 0, v36
	v_max_f32_e32 v38, 0, v38
	v_mul_f32_e32 v34, v34, v52
	v_mul_f32_e32 v35, v35, v52
	v_mul_f32_e32 v36, v36, v52
	v_max_f32_e32 v37, 0, v37
	v_mul_f32_e32 v38, v38, v52
	v_mul_f32_e32 v34, v34, v34
	v_mul_f32_e32 v35, v35, v35
	v_mul_f32_e32 v37, v37, v52
	v_mul_f32_e32 v36, v36, v36
	v_mul_f32_e32 v38, v38, v38
	v_mul_f32_e32 v37, v37, v37
	v_cvt_pk_bf16_f32 v34, v38, v34
	v_cvt_pk_bf16_f32 v35, v35, v36
	v_cvt_pk_bf16_f32 v36, v42, v39
	v_cvt_pk_bf16_f32 v37, v40, v37
	global_store_dwordx4 v[50:51], v[34:37], off offset:256 sc1
	ds_read_b32 v36, v148 offset:640
	v_max_f32_e32 v26, v26, v26
	v_max_f32_e32 v26, 0, v26
	v_max_f32_e32 v27, v27, v27
	v_max_f32_e32 v28, v28, v28
	s_waitcnt lgkmcnt(0)
	v_mul_f32_e32 v26, v26, v36
	v_max_f32_e32 v27, 0, v27
	v_max_f32_e32 v28, 0, v28
	v_max_f32_e32 v30, v30, v30
	v_mul_f32_e32 v37, v26, v26
	v_max_f32_e32 v26, v31, v31
	v_mul_f32_e32 v27, v27, v36
	v_mul_f32_e32 v28, v28, v36
	v_max_f32_e32 v30, 0, v30
	v_max_f32_e32 v26, 0, v26
	v_mul_f32_e32 v31, v27, v27
	v_max_f32_e32 v27, v32, v32
	v_mul_f32_e32 v32, v28, v28
	v_max_f32_e32 v28, v33, v33
	s_mov_b64 s[4:5], 0x280000
	v_mul_f32_e32 v30, v30, v36
	v_mul_f32_e32 v26, v26, v36
	v_max_f32_e32 v27, 0, v27
	v_max_f32_e32 v28, 0, v28
	v_max_f32_e32 v29, v29, v29
	v_lshl_add_u64 v[34:35], v[140:141], 0, s[4:5]
	v_mul_f32_e32 v30, v30, v30
	v_mul_f32_e32 v26, v26, v26
	v_mul_f32_e32 v27, v27, v36
	v_mul_f32_e32 v28, v28, v36
	v_max_f32_e32 v29, 0, v29
	s_mov_b32 s4, 0x280000
	v_max_f32_e32 v18, v18, v18
	v_max_f32_e32 v19, v19, v19
	v_max_f32_e32 v20, v20, v20
	v_mul_f32_e32 v27, v27, v27
	v_mul_f32_e32 v29, v29, v36
	v_mul_f32_e32 v28, v28, v28
	v_cvt_pk_bf16_f32 v26, v30, v26
	v_add_co_u32_e32 v30, vcc, s4, v140
	v_max_f32_e32 v18, 0, v18
	v_max_f32_e32 v19, 0, v19
	v_max_f32_e32 v20, 0, v20
	v_mul_f32_e32 v29, v29, v29
	v_cvt_pk_bf16_f32 v27, v27, v28
	v_cvt_pk_bf16_f32 v28, v37, v31
	v_addc_co_u32_e32 v31, vcc, 0, v141, vcc
	v_mul_f32_e32 v18, v18, v36
	v_mul_f32_e32 v19, v19, v36
	v_mul_f32_e32 v20, v20, v36
	v_cvt_pk_bf16_f32 v29, v32, v29
	global_store_dwordx4 v[30:31], v[26:29], off sc1
	v_max_f32_e32 v22, v22, v22
	v_max_f32_e32 v21, v21, v21
	v_mul_f32_e32 v26, v18, v18
	v_max_f32_e32 v18, v23, v23
	v_mul_f32_e32 v23, v19, v19
	v_max_f32_e32 v19, v24, v24
	v_mul_f32_e32 v24, v20, v20
	v_max_f32_e32 v20, v25, v25
	v_max_f32_e32 v18, 0, v18
	v_max_f32_e32 v19, 0, v19
	v_max_f32_e32 v20, 0, v20
	v_max_f32_e32 v22, 0, v22
	v_mul_f32_e32 v18, v18, v36
	v_mul_f32_e32 v19, v19, v36
	v_mul_f32_e32 v20, v20, v36
	v_max_f32_e32 v21, 0, v21
	v_mul_f32_e32 v22, v22, v36
	v_mul_f32_e32 v18, v18, v18
	v_mul_f32_e32 v19, v19, v19
	v_mul_f32_e32 v21, v21, v36
	v_mul_f32_e32 v20, v20, v20
	v_mul_f32_e32 v22, v22, v22
	v_mul_f32_e32 v21, v21, v21
	v_cvt_pk_bf16_f32 v18, v22, v18
	v_cvt_pk_bf16_f32 v19, v19, v20
	v_cvt_pk_bf16_f32 v20, v26, v23
	v_cvt_pk_bf16_f32 v21, v24, v21
	global_store_dwordx4 v[34:35], v[18:21], off offset:256 sc1
	ds_read_b32 v20, v148 offset:704
	v_max_f32_e32 v10, v10, v10
	v_max_f32_e32 v10, 0, v10
	v_max_f32_e32 v11, v11, v11
	v_max_f32_e32 v12, v12, v12
	s_waitcnt lgkmcnt(0)
	v_mul_f32_e32 v10, v10, v20
	v_max_f32_e32 v11, 0, v11
	v_max_f32_e32 v12, 0, v12
	v_max_f32_e32 v14, v14, v14
	v_mul_f32_e32 v21, v10, v10
	v_max_f32_e32 v10, v15, v15
	v_mul_f32_e32 v11, v11, v20
	v_mul_f32_e32 v12, v12, v20
	v_max_f32_e32 v14, 0, v14
	v_max_f32_e32 v10, 0, v10
	v_mul_f32_e32 v15, v11, v11
	v_max_f32_e32 v11, v16, v16
	v_mul_f32_e32 v16, v12, v12
	v_max_f32_e32 v12, v17, v17
	s_mov_b64 s[4:5], 0x2c0000
	v_mul_f32_e32 v14, v14, v20
	v_mul_f32_e32 v10, v10, v20
	v_max_f32_e32 v11, 0, v11
	v_max_f32_e32 v12, 0, v12
	v_max_f32_e32 v13, v13, v13
	v_lshl_add_u64 v[18:19], v[140:141], 0, s[4:5]
	v_mul_f32_e32 v14, v14, v14
	v_mul_f32_e32 v10, v10, v10
	v_mul_f32_e32 v11, v11, v20
	v_mul_f32_e32 v12, v12, v20
	v_max_f32_e32 v13, 0, v13
	s_mov_b32 s4, 0x2c0000
	v_max_f32_e32 v2, v2, v2
	v_max_f32_e32 v3, v3, v3
	v_max_f32_e32 v4, v4, v4
	v_mul_f32_e32 v11, v11, v11
	v_mul_f32_e32 v13, v13, v20
	v_mul_f32_e32 v12, v12, v12
	v_cvt_pk_bf16_f32 v10, v14, v10
	v_add_co_u32_e32 v14, vcc, s4, v140
	v_max_f32_e32 v2, 0, v2
	v_max_f32_e32 v3, 0, v3
	v_max_f32_e32 v4, 0, v4
	v_mul_f32_e32 v13, v13, v13
	v_cvt_pk_bf16_f32 v11, v11, v12
	v_cvt_pk_bf16_f32 v12, v21, v15
	v_addc_co_u32_e32 v15, vcc, 0, v141, vcc
	v_mul_f32_e32 v2, v2, v20
	v_mul_f32_e32 v3, v3, v20
	v_mul_f32_e32 v4, v4, v20
	v_cvt_pk_bf16_f32 v13, v16, v13
	global_store_dwordx4 v[14:15], v[10:13], off sc1
	v_max_f32_e32 v5, v5, v5
	v_max_f32_e32 v6, v6, v6
	v_mul_f32_e32 v10, v2, v2
	v_max_f32_e32 v2, v7, v7
	v_mul_f32_e32 v7, v3, v3
	v_max_f32_e32 v3, v8, v8
	v_mul_f32_e32 v8, v4, v4
	v_max_f32_e32 v4, v9, v9
	v_max_f32_e32 v2, 0, v2
	v_max_f32_e32 v3, 0, v3
	v_max_f32_e32 v4, 0, v4
	v_max_f32_e32 v5, 0, v5
	v_max_f32_e32 v6, 0, v6
	v_mul_f32_e32 v2, v2, v20
	v_mul_f32_e32 v3, v3, v20
	v_mul_f32_e32 v4, v4, v20
	v_mul_f32_e32 v5, v5, v20
	v_mul_f32_e32 v6, v6, v20
	v_mul_f32_e32 v2, v2, v2
	v_mul_f32_e32 v3, v3, v3
	v_mul_f32_e32 v4, v4, v4
	v_mul_f32_e32 v5, v5, v5
	s_mov_b64 s[4:5], -1
	s_andn2_b64 vcc, exec, s[40:41]
	v_mul_f32_e32 v6, v6, v6
	v_cvt_pk_bf16_f32 v2, v6, v2
	v_cvt_pk_bf16_f32 v3, v3, v4
	v_cvt_pk_bf16_f32 v4, v10, v7
	v_cvt_pk_bf16_f32 v5, v8, v5
	global_store_dwordx4 v[18:19], v[2:5], off offset:256 sc1
	s_cbranch_vccnz .LBB0_1329
	s_andn2_b64 vcc, exec, s[2:3]
	s_cbranch_vccnz .LBB0_1328
	s_barrier
	s_branch .LBB0_1328
